# diff unit tail: the 16 sub-layer-norm weight chunks loaded up front with one wait instead of a load plus full wait between consecutive output stores
# speedup vs baseline: 1.0059x; 1.0059x over previous
; DI void attn_diff_unit(const Params& p, int li, int b, int h, int qb, char* smem, bool pre, int nh, bool has_next) {
;     ...
;   }
;   __syncthreads();
;   if (map == 0) {
;     const float lam = ((const float*)(p.ws + TB_LAM))[li];
;     const int layer = 2 * li + 1;
;     const float linit = 0.8f - 0.6f * expf(-0.3f * (float)layer);
;     float ss = 0.f;
; #pragma unroll
;     for (int j = 0; j < 4; ++j)
; #pragma unroll
;       for (int i = 0; i < 16; ++i) {
;         float v = O[j][i] * inv - lam * xch[(rg * 64 + j * 16 + i) * 64 + lane];
;         O[j][i] = v; ss += v * v;
;       }
;     ss += shx(ss, 32, lane);
;     const float rinv = rsqrtf(ss * (1.f / 128.f) + EPS) * (1.f - linit);
;     const float* sub = p.c_subln + li * 128;
;     u16* op = o + (size_t)qrow * 1024 + h * 128 + 4 * hh;
; #pragma unroll
;     for (int j = 0; j < 4; ++j)
; #pragma unroll
;       for (int i4 = 0; i4 < 4; ++i4) {
;         const int dv = j * 32 + 8 * i4 + 4 * hh;
;         const f32x4 g4 = *(const f32x4*)(sub + dv);
.LBB0_596:
	s_or_b64 exec, exec, s[2:3]
	s_movk_i32 s2, 0x100
	v_cmp_gt_u32_e32 vcc, s2, v146
	s_waitcnt lgkmcnt(0)
	s_barrier
	s_and_saveexec_b64 s[2:3], vcc
	s_cbranch_execz .LBB0_560
	global_load_dword v72, v145, s[18:19]
	s_add_i32 s24, 0, 0x12800
	v_lshlrev_b32_e32 v70, 8, v146
	v_lshl_add_u32 v67, v158, 2, s24
	v_and_b32_e32 v64, 0xc000, v70
	v_add_u32_e32 v71, v67, v64
	s_waitcnt vmcnt(2)
	ds_read2st64_b32 v[130:131], v71 offset1:1
	ds_read2st64_b32 v[132:133], v71 offset0:2 offset1:3
	ds_read2st64_b32 v[126:127], v71 offset0:4 offset1:5
	ds_read2st64_b32 v[128:129], v71 offset0:6 offset1:7
	ds_read2st64_b32 v[122:123], v71 offset0:8 offset1:9
	ds_read2st64_b32 v[124:125], v71 offset0:10 offset1:11
	ds_read2st64_b32 v[118:119], v71 offset0:12 offset1:13
	ds_read2st64_b32 v[120:121], v71 offset0:14 offset1:15
	ds_read2st64_b32 v[114:115], v71 offset0:16 offset1:17
	ds_read2st64_b32 v[116:117], v71 offset0:18 offset1:19
	ds_read2st64_b32 v[110:111], v71 offset0:20 offset1:21
	ds_read2st64_b32 v[112:113], v71 offset0:22 offset1:23
	ds_read2st64_b32 v[106:107], v71 offset0:24 offset1:25
	ds_read2st64_b32 v[108:109], v71 offset0:26 offset1:27
	ds_read2st64_b32 v[102:103], v71 offset0:28 offset1:29
	ds_read2st64_b32 v[104:105], v71 offset0:30 offset1:31
	ds_read2st64_b32 v[98:99], v71 offset0:32 offset1:33
	ds_read2st64_b32 v[100:101], v71 offset0:34 offset1:35
	ds_read2st64_b32 v[94:95], v71 offset0:36 offset1:37
	ds_read2st64_b32 v[96:97], v71 offset0:38 offset1:39
	ds_read2st64_b32 v[90:91], v71 offset0:40 offset1:41
	ds_read2st64_b32 v[92:93], v71 offset0:42 offset1:43
	ds_read2st64_b32 v[86:87], v71 offset0:44 offset1:45
	ds_read2st64_b32 v[88:89], v71 offset0:46 offset1:47
	ds_read2st64_b32 v[82:83], v71 offset0:48 offset1:49
	ds_read2st64_b32 v[84:85], v71 offset0:50 offset1:51
	ds_read2st64_b32 v[78:79], v71 offset0:52 offset1:53
	ds_read2st64_b32 v[80:81], v71 offset0:54 offset1:55
	ds_read2st64_b32 v[74:75], v71 offset0:56 offset1:57
	ds_read2st64_b32 v[76:77], v71 offset0:58 offset1:59
	ds_read2st64_b32 v[64:65], v71 offset0:60 offset1:61
	v_lshlrev_b32_e32 v144, 1, v144
	s_lshl_b32 s24, s41, 1
	s_waitcnt vmcnt(0) lgkmcnt(0)
	v_pk_mul_f32 v[64:65], v[72:73], v[64:65] op_sel_hi:[0,1]
	v_pk_fma_f32 v[64:65], v[12:13], v[66:67], v[64:65] op_sel_hi:[1,0,1] neg_lo:[0,0,1] neg_hi:[0,0,1]
	v_or_b32_e32 v13, 0x3f00, v70
	v_add_u32_e32 v13, v67, v13
	ds_read_b32 v12, v71 offset:15872
	ds_read_b32 v13, v13
	v_pk_mul_f32 v[126:127], v[72:73], v[126:127] op_sel_hi:[0,1]
	v_pk_mul_f32 v[130:131], v[72:73], v[130:131] op_sel_hi:[0,1]
	v_pk_mul_f32 v[132:133], v[72:73], v[132:133] op_sel_hi:[0,1]
	v_pk_mul_f32 v[128:129], v[72:73], v[128:129] op_sel_hi:[0,1]
	s_waitcnt lgkmcnt(0)
	v_pk_mul_f32 v[12:13], v[72:73], v[12:13] op_sel_hi:[0,1]
	v_pk_fma_f32 v[12:13], v[14:15], v[66:67], v[12:13] op_sel_hi:[1,0,1] neg_lo:[0,0,1] neg_hi:[0,0,1]
	v_lshlrev_b32_e32 v67, 2, v153
	global_load_dwordx4 v[134:137], v67, s[20:21]
	global_load_dwordx4 v[196:199], v67, s[20:21] offset:32
	global_load_dwordx4 v[200:203], v67, s[20:21] offset:64
	global_load_dwordx4 v[204:207], v67, s[20:21] offset:96
	global_load_dwordx4 v[208:211], v67, s[20:21] offset:128
	global_load_dwordx4 v[212:215], v67, s[20:21] offset:160
	global_load_dwordx4 v[216:219], v67, s[20:21] offset:192
	global_load_dwordx4 v[220:223], v67, s[20:21] offset:224
	global_load_dwordx4 v[224:227], v67, s[20:21] offset:256
	global_load_dwordx4 v[228:231], v67, s[20:21] offset:288
	global_load_dwordx4 v[232:235], v67, s[20:21] offset:320
	global_load_dwordx4 v[160:163], v67, s[20:21] offset:352
	global_load_dwordx4 v[164:167], v67, s[20:21] offset:384
	global_load_dwordx4 v[168:171], v67, s[20:21] offset:416
	global_load_dwordx4 v[172:175], v67, s[20:21] offset:448
	global_load_dwordx4 v[176:179], v67, s[20:21] offset:480
	v_pk_fma_f32 v[126:127], v[52:53], v[66:67], v[126:127] op_sel_hi:[1,0,1] neg_lo:[0,0,1] neg_hi:[0,0,1]
	v_pk_mul_f32 v[52:53], v[72:73], v[124:125] op_sel_hi:[0,1]
	v_pk_fma_f32 v[52:53], v[58:59], v[66:67], v[52:53] op_sel_hi:[1,0,1] neg_lo:[0,0,1] neg_hi:[0,0,1]
	v_pk_mul_f32 v[58:59], v[72:73], v[122:123] op_sel_hi:[0,1]
	v_pk_fma_f32 v[58:59], v[56:57], v[66:67], v[58:59] op_sel_hi:[1,0,1] neg_lo:[0,0,1] neg_hi:[0,0,1]
	v_pk_mul_f32 v[56:57], v[72:73], v[120:121] op_sel_hi:[0,1]
	v_pk_fma_f32 v[56:57], v[62:63], v[66:67], v[56:57] op_sel_hi:[1,0,1] neg_lo:[0,0,1] neg_hi:[0,0,1]
	v_pk_mul_f32 v[62:63], v[72:73], v[118:119] op_sel_hi:[0,1]
	v_pk_fma_f32 v[60:61], v[60:61], v[66:67], v[62:63] op_sel_hi:[1,0,1] neg_lo:[0,0,1] neg_hi:[0,0,1]
	v_pk_mul_f32 v[62:63], v[72:73], v[116:117] op_sel_hi:[0,1]
	v_pk_fma_f32 v[34:35], v[34:35], v[66:67], v[62:63] op_sel_hi:[1,0,1] neg_lo:[0,0,1] neg_hi:[0,0,1]
	v_pk_mul_f32 v[62:63], v[72:73], v[114:115] op_sel_hi:[0,1]
	v_pk_fma_f32 v[32:33], v[32:33], v[66:67], v[62:63] op_sel_hi:[1,0,1] neg_lo:[0,0,1] neg_hi:[0,0,1]
	v_pk_mul_f32 v[62:63], v[72:73], v[112:113] op_sel_hi:[0,1]
	v_pk_fma_f32 v[38:39], v[38:39], v[66:67], v[62:63] op_sel_hi:[1,0,1] neg_lo:[0,0,1] neg_hi:[0,0,1]
	v_pk_mul_f32 v[62:63], v[72:73], v[110:111] op_sel_hi:[0,1]
	v_pk_fma_f32 v[110:111], v[36:37], v[66:67], v[62:63] op_sel_hi:[1,0,1] neg_lo:[0,0,1] neg_hi:[0,0,1]
	v_pk_mul_f32 v[36:37], v[72:73], v[108:109] op_sel_hi:[0,1]
	v_pk_fma_f32 v[62:63], v[42:43], v[66:67], v[36:37] op_sel_hi:[1,0,1] neg_lo:[0,0,1] neg_hi:[0,0,1]
	v_pk_mul_f32 v[36:37], v[72:73], v[106:107] op_sel_hi:[0,1]
	v_pk_fma_f32 v[106:107], v[40:41], v[66:67], v[36:37] op_sel_hi:[1,0,1] neg_lo:[0,0,1] neg_hi:[0,0,1]
	v_pk_mul_f32 v[36:37], v[72:73], v[104:105] op_sel_hi:[0,1]
; DI void attn_diff_unit(const Params& p, int li, int b, int h, int qb, char* smem, bool pre, int nh, bool has_next) {
;     ...
; #pragma unroll
;     for (int j = 0; j < 4; ++j)
; #pragma unroll
;       for (int i = 0; i < 16; ++i) {
;         float v = O[j][i] * inv - lam * xch[(rg * 64 + j * 16 + i) * 64 + lane];
;         O[j][i] = v; ss += v * v;
;       }
;     ss += shx(ss, 32, lane);
;     const float rinv = rsqrtf(ss * (1.f / 128.f) + EPS) * (1.f - linit);
	v_pk_fma_f32 v[46:47], v[46:47], v[66:67], v[36:37] op_sel_hi:[1,0,1] neg_lo:[0,0,1] neg_hi:[0,0,1]
	v_pk_mul_f32 v[36:37], v[72:73], v[102:103] op_sel_hi:[0,1]
	v_pk_fma_f32 v[102:103], v[44:45], v[66:67], v[36:37] op_sel_hi:[1,0,1] neg_lo:[0,0,1] neg_hi:[0,0,1]
	v_pk_mul_f32 v[36:37], v[72:73], v[100:101] op_sel_hi:[0,1]
	v_pk_fma_f32 v[40:41], v[18:19], v[66:67], v[36:37] op_sel_hi:[1,0,1] neg_lo:[0,0,1] neg_hi:[0,0,1]
	v_pk_mul_f32 v[18:19], v[72:73], v[98:99] op_sel_hi:[0,1]
	v_pk_fma_f32 v[44:45], v[16:17], v[66:67], v[18:19] op_sel_hi:[1,0,1] neg_lo:[0,0,1] neg_hi:[0,0,1]
	v_pk_mul_f32 v[16:17], v[72:73], v[96:97] op_sel_hi:[0,1]
	v_pk_fma_f32 v[36:37], v[22:23], v[66:67], v[16:17] op_sel_hi:[1,0,1] neg_lo:[0,0,1] neg_hi:[0,0,1]
	v_pk_mul_f32 v[16:17], v[72:73], v[94:95] op_sel_hi:[0,1]
	v_pk_fma_f32 v[42:43], v[20:21], v[66:67], v[16:17] op_sel_hi:[1,0,1] neg_lo:[0,0,1] neg_hi:[0,0,1]
	v_pk_mul_f32 v[16:17], v[72:73], v[92:93] op_sel_hi:[0,1]
	v_pk_fma_f32 v[22:23], v[26:27], v[66:67], v[16:17] op_sel_hi:[1,0,1] neg_lo:[0,0,1] neg_hi:[0,0,1]
	v_pk_mul_f32 v[16:17], v[72:73], v[90:91] op_sel_hi:[0,1]
	v_pk_fma_f32 v[26:27], v[24:25], v[66:67], v[16:17] op_sel_hi:[1,0,1] neg_lo:[0,0,1] neg_hi:[0,0,1]
	v_pk_mul_f32 v[16:17], v[72:73], v[88:89] op_sel_hi:[0,1]
	v_pk_fma_f32 v[18:19], v[30:31], v[66:67], v[16:17] op_sel_hi:[1,0,1] neg_lo:[0,0,1] neg_hi:[0,0,1]
	v_pk_mul_f32 v[16:17], v[72:73], v[86:87] op_sel_hi:[0,1]
	v_pk_fma_f32 v[24:25], v[28:29], v[66:67], v[16:17] op_sel_hi:[1,0,1] neg_lo:[0,0,1] neg_hi:[0,0,1]
	v_pk_mul_f32 v[16:17], v[72:73], v[84:85] op_sel_hi:[0,1]
	v_pk_fma_f32 v[16:17], v[2:3], v[66:67], v[16:17] op_sel_hi:[1,0,1] neg_lo:[0,0,1] neg_hi:[0,0,1]
	v_pk_mul_f32 v[2:3], v[72:73], v[82:83] op_sel_hi:[0,1]
	v_pk_fma_f32 v[20:21], v[0:1], v[66:67], v[2:3] op_sel_hi:[1,0,1] neg_lo:[0,0,1] neg_hi:[0,0,1]
	v_pk_mul_f32 v[0:1], v[72:73], v[80:81] op_sel_hi:[0,1]
	v_pk_fma_f32 v[48:49], v[48:49], v[66:67], v[130:131] op_sel_hi:[1,0,1] neg_lo:[0,0,1] neg_hi:[0,0,1]
	v_pk_fma_f32 v[2:3], v[6:7], v[66:67], v[0:1] op_sel_hi:[1,0,1] neg_lo:[0,0,1] neg_hi:[0,0,1]
	v_pk_mul_f32 v[0:1], v[72:73], v[78:79] op_sel_hi:[0,1]
	v_pk_fma_f32 v[50:51], v[50:51], v[66:67], v[132:133] op_sel_hi:[1,0,1] neg_lo:[0,0,1] neg_hi:[0,0,1]
	v_pk_mul_f32 v[130:131], v[48:49], v[48:49]
	v_pk_fma_f32 v[6:7], v[4:5], v[66:67], v[0:1] op_sel_hi:[1,0,1] neg_lo:[0,0,1] neg_hi:[0,0,1]
	v_pk_mul_f32 v[0:1], v[72:73], v[76:77] op_sel_hi:[0,1]
	v_pk_mul_f32 v[4:5], v[72:73], v[74:75] op_sel_hi:[0,1]
	v_pk_mul_f32 v[132:133], v[50:51], v[50:51]
	v_pk_fma_f32 v[54:55], v[54:55], v[66:67], v[128:129] op_sel_hi:[1,0,1] neg_lo:[0,0,1] neg_hi:[0,0,1]
	v_pk_fma_f32 v[0:1], v[10:11], v[66:67], v[0:1] op_sel_hi:[1,0,1] neg_lo:[0,0,1] neg_hi:[0,0,1]
	v_pk_fma_f32 v[4:5], v[8:9], v[66:67], v[4:5] op_sel_hi:[1,0,1] neg_lo:[0,0,1] neg_hi:[0,0,1]
	v_add_f32_e32 v66, v130, v131
	v_add_f32_e32 v66, v66, v132
	v_add_f32_e32 v66, v66, v133
	v_pk_mul_f32 v[128:129], v[54:55], v[54:55]
	v_pk_mul_f32 v[122:123], v[58:59], v[58:59]
	v_pk_mul_f32 v[124:125], v[52:53], v[52:53]
	v_pk_mul_f32 v[118:119], v[60:61], v[60:61]
	v_pk_mul_f32 v[120:121], v[56:57], v[56:57]
	v_pk_mul_f32 v[114:115], v[32:33], v[32:33]
	v_pk_mul_f32 v[116:117], v[34:35], v[34:35]
	v_pk_mul_f32 v[112:113], v[38:39], v[38:39]
	v_pk_mul_f32 v[138:139], v[106:107], v[106:107]
	v_pk_mul_f32 v[108:109], v[62:63], v[62:63]
	v_pk_mul_f32 v[140:141], v[102:103], v[102:103]
	v_pk_mul_f32 v[104:105], v[46:47], v[46:47]
	v_pk_mul_f32 v[98:99], v[44:45], v[44:45]
	v_pk_mul_f32 v[100:101], v[40:41], v[40:41]
	v_pk_mul_f32 v[94:95], v[42:43], v[42:43]
	v_pk_mul_f32 v[96:97], v[36:37], v[36:37]
	v_pk_mul_f32 v[90:91], v[26:27], v[26:27]
	v_pk_mul_f32 v[92:93], v[22:23], v[22:23]
	s_waitcnt vmcnt(0)
	v_pk_mul_f32 v[48:49], v[48:49], v[134:135]
	v_pk_mul_f32 v[134:135], v[126:127], v[126:127]
	v_pk_mul_f32 v[50:51], v[50:51], v[136:137]
	v_add_f32_e32 v66, v66, v134
	v_add_f32_e32 v66, v66, v135
	v_add_f32_e32 v66, v66, v128
	v_add_f32_e32 v66, v66, v129
	v_add_f32_e32 v66, v66, v122
	v_add_f32_e32 v66, v66, v123
	v_add_f32_e32 v66, v66, v124
	v_add_f32_e32 v66, v66, v125
	v_add_f32_e32 v66, v66, v118
	v_add_f32_e32 v66, v66, v119
	v_add_f32_e32 v66, v66, v120
	v_add_f32_e32 v66, v66, v121
	v_add_f32_e32 v66, v66, v114
	v_add_f32_e32 v66, v66, v115
	v_add_f32_e32 v66, v66, v116
	v_pk_mul_f32 v[136:137], v[110:111], v[110:111]
	v_add_f32_e32 v66, v66, v117
	v_add_f32_e32 v66, v66, v136
	v_add_f32_e32 v66, v66, v137
	v_add_f32_e32 v66, v66, v112
	v_add_f32_e32 v66, v66, v113
	v_add_f32_e32 v66, v66, v138
	v_add_f32_e32 v66, v66, v139
	v_add_f32_e32 v66, v66, v108
	v_add_f32_e32 v66, v66, v109
	v_add_f32_e32 v66, v66, v140
	v_add_f32_e32 v66, v66, v141
	v_add_f32_e32 v66, v66, v104
	v_add_f32_e32 v66, v66, v105
	v_add_f32_e32 v66, v66, v98
	v_add_f32_e32 v66, v66, v99
	v_add_f32_e32 v66, v66, v100
	v_add_f32_e32 v66, v66, v101
	v_add_f32_e32 v66, v66, v94
	v_add_f32_e32 v66, v66, v95
	v_add_f32_e32 v66, v66, v96
	v_add_f32_e32 v66, v66, v97
	v_add_f32_e32 v66, v66, v90
	v_add_f32_e32 v66, v66, v91
	v_add_f32_e32 v66, v66, v92
	v_pk_mul_f32 v[28:29], v[24:25], v[24:25]
	v_add_f32_e32 v66, v66, v93
	v_add_f32_e32 v28, v66, v28
	v_pk_mul_f32 v[30:31], v[18:19], v[18:19]
	v_add_f32_e32 v28, v28, v29
	v_add_f32_e32 v28, v28, v30
	v_pk_mul_f32 v[82:83], v[20:21], v[20:21]
	v_add_f32_e32 v28, v28, v31
	v_add_f32_e32 v28, v28, v82
	v_pk_mul_f32 v[84:85], v[16:17], v[16:17]
	v_add_f32_e32 v28, v28, v83
	v_add_f32_e32 v28, v28, v84
	v_pk_mul_f32 v[78:79], v[6:7], v[6:7]
	v_add_f32_e32 v28, v28, v85
	v_add_f32_e32 v28, v28, v78
	v_pk_mul_f32 v[80:81], v[2:3], v[2:3]
	v_add_f32_e32 v28, v28, v79
	v_add_f32_e32 v28, v28, v80
	v_pk_mul_f32 v[8:9], v[4:5], v[4:5]
	v_add_f32_e32 v28, v28, v81
	v_add_f32_e32 v8, v28, v8
	v_pk_mul_f32 v[10:11], v[0:1], v[0:1]
	v_add_f32_e32 v8, v8, v9
	v_add_f32_e32 v8, v8, v10
	v_pk_mul_f32 v[68:69], v[64:65], v[64:65]
	v_add_f32_e32 v8, v8, v11
	v_add_f32_e32 v8, v8, v68
	v_pk_mul_f32 v[70:71], v[12:13], v[12:13]
	v_add_f32_e32 v8, v8, v69
	v_add_f32_e32 v8, v8, v70
	v_add_f32_e32 v8, v8, v71
	ds_bpermute_b32 v9, v147, v8
	v_lshl_add_u64 v[14:15], s[16:17], 0, v[144:145]
	v_lshl_add_u64 v[14:15], v[14:15], 0, s[24:25]
	s_mov_b32 s24, 0x800000
	v_lshlrev_b32_e32 v144, 1, v153
	s_waitcnt lgkmcnt(0)
; DI void attn_diff_unit(const Params& p, int li, int b, int h, int qb, char* smem, bool pre, int nh, bool has_next) {
;     ...
;     const float rinv = rsqrtf(ss * (1.f / 128.f) + EPS) * (1.f - linit);
;     const float* sub = p.c_subln + li * 128;
;     u16* op = o + (size_t)qrow * 1024 + h * 128 + 4 * hh;
; #pragma unroll
;     for (int j = 0; j < 4; ++j)
; #pragma unroll
;       for (int i4 = 0; i4 < 4; ++i4) {
;         const int dv = j * 32 + 8 * i4 + 4 * hh;
;         const f32x4 g4 = *(const f32x4*)(sub + dv);
;         f32x4 v = {O[j][4 * i4] * g4[0], O[j][4 * i4 + 1] * g4[1], O[j][4 * i4 + 2] * g4[2], O[j][4 * i4 + 3] * g4[3]};
;         st_bf4(op + j * 32 + 8 * i4, v, rinv);
;       }
	v_add_f32_e32 v8, v8, v9
	v_fmamk_f32 v8, v8, 0x3c000000, v184
	v_cmp_gt_f32_e32 vcc, s24, v8
	v_mul_f32_e32 v9, 0x4b800000, v8
	v_lshl_add_u64 v[14:15], v[14:15], 0, v[144:145]
	v_cndmask_b32_e32 v8, v8, v9, vcc
	v_rsq_f32_e32 v8, v8
	s_nop 0
	v_mul_f32_e32 v9, 0x45800000, v8
	v_cndmask_b32_e32 v8, v8, v9, vcc
	v_mul_f32_e32 v8, v152, v8
	v_pk_mul_f32 v[10:11], v[48:49], v[8:9] op_sel_hi:[1,0]
	v_pk_mul_f32 v[28:29], v[50:51], v[8:9] op_sel_hi:[1,0]
	v_cvt_pk_bf16_f32 v10, v10, v11
	v_cvt_pk_bf16_f32 v11, v28, v29
	global_store_dwordx2 v[14:15], v[10:11], off
	v_pk_mul_f32 v[10:11], v[126:127], v[196:197]
	v_pk_mul_f32 v[28:29], v[54:55], v[198:199]
	v_pk_mul_f32 v[10:11], v[10:11], v[8:9] op_sel_hi:[1,0]
	v_pk_mul_f32 v[28:29], v[28:29], v[8:9] op_sel_hi:[1,0]
	v_cvt_pk_bf16_f32 v10, v10, v11
	v_cvt_pk_bf16_f32 v11, v28, v29
	global_store_dwordx2 v[14:15], v[10:11], off offset:16
	v_pk_mul_f32 v[10:11], v[58:59], v[200:201]
	v_pk_mul_f32 v[28:29], v[52:53], v[202:203]
	v_pk_mul_f32 v[10:11], v[10:11], v[8:9] op_sel_hi:[1,0]
	v_pk_mul_f32 v[28:29], v[28:29], v[8:9] op_sel_hi:[1,0]
	v_cvt_pk_bf16_f32 v10, v10, v11
	v_cvt_pk_bf16_f32 v11, v28, v29
	global_store_dwordx2 v[14:15], v[10:11], off offset:32
	v_pk_mul_f32 v[10:11], v[60:61], v[204:205]
	v_pk_mul_f32 v[28:29], v[56:57], v[206:207]
	v_pk_mul_f32 v[10:11], v[10:11], v[8:9] op_sel_hi:[1,0]
	v_pk_mul_f32 v[28:29], v[28:29], v[8:9] op_sel_hi:[1,0]
	v_cvt_pk_bf16_f32 v10, v10, v11
	v_cvt_pk_bf16_f32 v11, v28, v29
	global_store_dwordx2 v[14:15], v[10:11], off offset:48
	v_pk_mul_f32 v[10:11], v[32:33], v[208:209]
	v_pk_mul_f32 v[28:29], v[34:35], v[210:211]
	v_pk_mul_f32 v[10:11], v[10:11], v[8:9] op_sel_hi:[1,0]
	v_pk_mul_f32 v[28:29], v[28:29], v[8:9] op_sel_hi:[1,0]
	v_cvt_pk_bf16_f32 v10, v10, v11
	v_cvt_pk_bf16_f32 v11, v28, v29
	global_store_dwordx2 v[14:15], v[10:11], off offset:64
	v_pk_mul_f32 v[10:11], v[110:111], v[212:213]
	v_pk_mul_f32 v[28:29], v[38:39], v[214:215]
	v_pk_mul_f32 v[10:11], v[8:9], v[10:11] op_sel_hi:[0,1]
	v_pk_mul_f32 v[28:29], v[8:9], v[28:29] op_sel_hi:[0,1]
	v_cvt_pk_bf16_f32 v10, v10, v11
	v_cvt_pk_bf16_f32 v11, v28, v29
	global_store_dwordx2 v[14:15], v[10:11], off offset:80
	v_pk_mul_f32 v[10:11], v[106:107], v[216:217]
	v_pk_mul_f32 v[28:29], v[62:63], v[218:219]
	v_pk_mul_f32 v[10:11], v[8:9], v[10:11] op_sel_hi:[0,1]
	v_pk_mul_f32 v[28:29], v[8:9], v[28:29] op_sel_hi:[0,1]
	v_cvt_pk_bf16_f32 v10, v10, v11
	v_cvt_pk_bf16_f32 v11, v28, v29
	global_store_dwordx2 v[14:15], v[10:11], off offset:96
	v_pk_mul_f32 v[10:11], v[102:103], v[220:221]
	v_pk_mul_f32 v[28:29], v[46:47], v[222:223]
	v_pk_mul_f32 v[10:11], v[8:9], v[10:11] op_sel_hi:[0,1]
	v_pk_mul_f32 v[28:29], v[8:9], v[28:29] op_sel_hi:[0,1]
	v_cvt_pk_bf16_f32 v10, v10, v11
	v_cvt_pk_bf16_f32 v11, v28, v29
	global_store_dwordx2 v[14:15], v[10:11], off offset:112
	v_pk_mul_f32 v[10:11], v[44:45], v[224:225]
	v_pk_mul_f32 v[28:29], v[40:41], v[226:227]
	v_pk_mul_f32 v[10:11], v[8:9], v[10:11] op_sel_hi:[0,1]
	v_pk_mul_f32 v[28:29], v[8:9], v[28:29] op_sel_hi:[0,1]
	v_cvt_pk_bf16_f32 v10, v10, v11
	v_cvt_pk_bf16_f32 v11, v28, v29
	global_store_dwordx2 v[14:15], v[10:11], off offset:128
	v_pk_mul_f32 v[10:11], v[42:43], v[228:229]
	v_pk_mul_f32 v[28:29], v[36:37], v[230:231]
	v_pk_mul_f32 v[10:11], v[8:9], v[10:11] op_sel_hi:[0,1]
	v_pk_mul_f32 v[28:29], v[8:9], v[28:29] op_sel_hi:[0,1]
	v_cvt_pk_bf16_f32 v10, v10, v11
	v_cvt_pk_bf16_f32 v11, v28, v29
	global_store_dwordx2 v[14:15], v[10:11], off offset:144
	v_pk_mul_f32 v[10:11], v[26:27], v[232:233]
	v_pk_mul_f32 v[22:23], v[22:23], v[234:235]
	v_pk_mul_f32 v[10:11], v[8:9], v[10:11] op_sel_hi:[0,1]
	v_pk_mul_f32 v[22:23], v[8:9], v[22:23] op_sel_hi:[0,1]
	v_cvt_pk_bf16_f32 v10, v10, v11
	v_cvt_pk_bf16_f32 v11, v22, v23
	global_store_dwordx2 v[14:15], v[10:11], off offset:160
	v_pk_mul_f32 v[10:11], v[24:25], v[160:161]
	v_pk_mul_f32 v[18:19], v[18:19], v[162:163]
	v_pk_mul_f32 v[10:11], v[8:9], v[10:11] op_sel_hi:[0,1]
	v_pk_mul_f32 v[18:19], v[8:9], v[18:19] op_sel_hi:[0,1]
	v_cvt_pk_bf16_f32 v10, v10, v11
	v_cvt_pk_bf16_f32 v11, v18, v19
	global_store_dwordx2 v[14:15], v[10:11], off offset:176
	v_pk_mul_f32 v[10:11], v[20:21], v[164:165]
	v_pk_mul_f32 v[16:17], v[16:17], v[166:167]
	v_pk_mul_f32 v[10:11], v[8:9], v[10:11] op_sel_hi:[0,1]
	v_pk_mul_f32 v[16:17], v[8:9], v[16:17] op_sel_hi:[0,1]
	v_cvt_pk_bf16_f32 v10, v10, v11
	v_cvt_pk_bf16_f32 v11, v16, v17
	global_store_dwordx2 v[14:15], v[10:11], off offset:192
	v_pk_mul_f32 v[6:7], v[6:7], v[168:169]
	v_pk_mul_f32 v[2:3], v[2:3], v[170:171]
	v_pk_mul_f32 v[6:7], v[8:9], v[6:7] op_sel_hi:[0,1]
	v_pk_mul_f32 v[2:3], v[8:9], v[2:3] op_sel_hi:[0,1]
	v_cvt_pk_bf16_f32 v6, v6, v7
	v_cvt_pk_bf16_f32 v7, v2, v3
	global_store_dwordx2 v[14:15], v[6:7], off offset:208
	v_pk_mul_f32 v[2:3], v[4:5], v[172:173]
	v_pk_mul_f32 v[0:1], v[0:1], v[174:175]
	v_pk_mul_f32 v[2:3], v[8:9], v[2:3] op_sel_hi:[0,1]
	v_pk_mul_f32 v[0:1], v[8:9], v[0:1] op_sel_hi:[0,1]
	v_cvt_pk_bf16_f32 v2, v2, v3
	v_cvt_pk_bf16_f32 v3, v0, v1
	global_store_dwordx2 v[14:15], v[2:3], off offset:224
	v_pk_mul_f32 v[0:1], v[64:65], v[176:177]
	v_pk_mul_f32 v[2:3], v[12:13], v[178:179]
	v_pk_mul_f32 v[0:1], v[8:9], v[0:1] op_sel_hi:[0,1]
	v_pk_mul_f32 v[2:3], v[8:9], v[2:3] op_sel_hi:[0,1]
	v_cvt_pk_bf16_f32 v0, v0, v1
	v_cvt_pk_bf16_f32 v1, v2, v3
	global_store_dwordx2 v[14:15], v[0:1], off offset:240
	s_branch .LBB0_560
